# P5 epilogue: the 16 cross-row ds_bpermute reductions (xor 16, xor 32) replaced by v_permlane16_swap / v_permlane32_swap
# baseline (speedup 1.0000x reference)
.LBB0_548:
	v_lshl_add_u32 v142, s50, 8, v144
	v_lshl_or_b32 v140, s12, 8, v146
	v_ashrrev_i32_e32 v143, 31, v142
	v_ashrrev_i32_e32 v141, 31, v140
	v_lshlrev_b64 v[152:153], 11, v[142:143]
	v_lshl_add_u64 v[152:153], v[152:153], 0, v[140:141]
	v_lshlrev_b64 v[152:153], 1, v[152:153]
	v_lshl_add_u64 v[154:155], s[18:19], 0, v[152:153]
	global_load_dwordx2 v[156:157], v[154:155], off
	global_load_dwordx2 v[158:159], v[154:155], off offset:32
	global_load_dwordx2 v[160:161], v[154:155], off offset:256
	s_nop 0
	global_load_dwordx2 v[154:155], v[154:155], off offset:288
	v_and_b32_e32 v162, 64, v150
	v_xor_b32_e32 v151, 16, v150
	v_add_u32_e32 v162, 64, v162
	v_xor_b32_e32 v163, 32, v150
	v_cmp_lt_i32_e32 vcc, v151, v162
	v_lshl_add_u64 v[152:153], s[10:11], 0, v[152:153]
	s_lshl_b32 s50, s12, 2
	v_cndmask_b32_e32 v151, v150, v151, vcc
	v_cmp_lt_i32_e32 vcc, v163, v162
	v_lshlrev_b32_e32 v151, 2, v151
	s_ashr_i32 s51, s50, 31
	v_cndmask_b32_e32 v170, v150, v163, vcc
	s_waitcnt vmcnt(0)
	v_lshlrev_b32_e32 v162, 16, v156
	v_and_b32_e32 v163, 0xffff0000, v156
	v_lshlrev_b32_e32 v156, 16, v157
	v_and_b32_e32 v157, 0xffff0000, v157
	v_lshlrev_b32_e32 v164, 16, v158
	v_and_b32_e32 v165, 0xffff0000, v158
	v_lshlrev_b32_e32 v158, 16, v159
	v_and_b32_e32 v159, 0xffff0000, v159
	v_lshlrev_b32_e32 v166, 16, v160
	v_and_b32_e32 v167, 0xffff0000, v160
	v_lshlrev_b32_e32 v160, 16, v161
	v_and_b32_e32 v161, 0xffff0000, v161
	v_lshlrev_b32_e32 v168, 16, v154
	v_and_b32_e32 v169, 0xffff0000, v154
	v_lshlrev_b32_e32 v154, 16, v155
	v_and_b32_e32 v155, 0xffff0000, v155
	v_pk_add_f32 v[126:127], v[126:127], v[156:157]
	v_pk_add_f32 v[124:125], v[124:125], v[162:163]
	v_pk_add_f32 v[122:123], v[122:123], v[158:159]
	v_pk_add_f32 v[120:121], v[120:121], v[164:165]
	v_pk_add_f32 v[118:119], v[118:119], v[160:161]
	v_pk_add_f32 v[116:117], v[116:117], v[166:167]
	v_pk_add_f32 v[154:155], v[114:115], v[154:155]
	v_pk_add_f32 v[156:157], v[112:113], v[168:169]
	v_mul_f32_e32 v114, v125, v125
	v_mul_f32_e32 v115, v127, v127
	v_cvt_pk_bf16_f32 v112, v124, v125
	v_cvt_pk_bf16_f32 v113, v126, v127
	v_mul_f32_e32 v125, v121, v121
	v_mul_f32_e32 v127, v123, v123
	v_mul_f32_e32 v158, v117, v117
	v_mul_f32_e32 v159, v119, v119
	v_fmac_f32_e32 v114, v124, v124
	v_fmac_f32_e32 v115, v126, v126
	v_fmac_f32_e32 v125, v120, v120
	v_fmac_f32_e32 v127, v122, v122
	v_mul_f32_e32 v160, v157, v157
	v_mul_f32_e32 v161, v155, v155
	global_store_dwordx2 v[152:153], v[112:113], off
	v_fmac_f32_e32 v158, v116, v116
	v_fmac_f32_e32 v159, v118, v118
	v_add_f32_e32 v113, v114, v115
	v_add_f32_e32 v114, v125, v127
	v_fmac_f32_e32 v160, v156, v156
	v_fmac_f32_e32 v161, v154, v154
	v_add_f32_e32 v115, v158, v159
	v_add_f32_e32 v113, v113, v114
	v_cvt_pk_bf16_f32 v112, v120, v121
	v_add_f32_e32 v120, v160, v161
	v_add_f32_e32 v113, v113, v115
	v_add_f32_e32 v114, v113, v120
	v_mov_b32_e32 v115, v114
	s_nop 1
	v_permlane16_swap_b32_e32 v114, v115
	v_cvt_pk_bf16_f32 v113, v122, v123
	global_store_dwordx2 v[152:153], v[112:113], off offset:32
	v_cvt_pk_bf16_f32 v116, v116, v117
	v_cvt_pk_bf16_f32 v117, v118, v119
	s_waitcnt lgkmcnt(0)
	v_add_f32_e32 v112, v114, v115
	v_lshlrev_b32_e32 v114, 2, v170
	v_mov_b32_e32 v113, v112
	s_nop 1
	v_permlane32_swap_b32_e32 v112, v113
	global_store_dwordx2 v[152:153], v[116:117], off offset:256
	v_cvt_pk_bf16_f32 v116, v156, v157
	v_cvt_pk_bf16_f32 v117, v154, v155
	global_store_dwordx2 v[152:153], v[116:117], off offset:288
	s_and_saveexec_b64 s[54:55], s[0:1]
	s_cbranch_execz .LBB0_550
	v_lshlrev_b64 v[116:117], 7, v[142:143]
	v_lshl_add_u64 v[116:117], s[26:27], 0, v[116:117]
	v_lshl_add_u64 v[116:117], s[50:51], 2, v[116:117]
	s_lshl_b32 s12, s64, 2
	v_lshl_add_u64 v[116:117], v[116:117], 0, s[12:13]
	s_waitcnt lgkmcnt(0)
	v_add_f32_e32 v112, v112, v113
	global_store_dword v[116:117], v112, off
.LBB0_550:
	s_or_b64 exec, exec, s[54:55]
	v_or_b32_e32 v112, 16, v142
	s_waitcnt lgkmcnt(0)
	v_ashrrev_i32_e32 v113, 31, v112
	v_lshlrev_b64 v[116:117], 11, v[112:113]
	v_lshl_add_u64 v[116:117], v[116:117], 0, v[140:141]
	v_lshlrev_b64 v[116:117], 1, v[116:117]
	v_lshl_add_u64 v[118:119], s[18:19], 0, v[116:117]
	global_load_dwordx2 v[120:121], v[118:119], off
	global_load_dwordx2 v[122:123], v[118:119], off offset:32
	global_load_dwordx2 v[124:125], v[118:119], off offset:256
	s_nop 0
	global_load_dwordx2 v[118:119], v[118:119], off offset:288
	v_lshl_add_u64 v[116:117], s[10:11], 0, v[116:117]
	s_waitcnt vmcnt(3)
	v_lshlrev_b32_e32 v126, 16, v120
	v_and_b32_e32 v127, 0xffff0000, v120
	v_lshlrev_b32_e32 v120, 16, v121
	v_and_b32_e32 v121, 0xffff0000, v121
	s_waitcnt vmcnt(2)
	v_lshlrev_b32_e32 v152, 16, v122
	v_and_b32_e32 v153, 0xffff0000, v122
	v_lshlrev_b32_e32 v122, 16, v123
	v_and_b32_e32 v123, 0xffff0000, v123
	s_waitcnt vmcnt(1)
	v_lshlrev_b32_e32 v154, 16, v124
	v_and_b32_e32 v155, 0xffff0000, v124
	v_lshlrev_b32_e32 v124, 16, v125
	v_and_b32_e32 v125, 0xffff0000, v125
	s_waitcnt vmcnt(0)
	v_lshlrev_b32_e32 v156, 16, v118
	v_and_b32_e32 v157, 0xffff0000, v118
	v_lshlrev_b32_e32 v118, 16, v119
	v_and_b32_e32 v119, 0xffff0000, v119
	v_pk_add_f32 v[110:111], v[110:111], v[120:121]
	v_pk_add_f32 v[108:109], v[108:109], v[126:127]
	v_pk_add_f32 v[106:107], v[106:107], v[122:123]
	v_pk_add_f32 v[104:105], v[104:105], v[152:153]
	v_pk_add_f32 v[102:103], v[102:103], v[124:125]
	v_pk_add_f32 v[100:101], v[100:101], v[154:155]
	v_pk_add_f32 v[98:99], v[98:99], v[118:119]
	v_pk_add_f32 v[118:119], v[96:97], v[156:157]
	v_mul_f32_e32 v115, v109, v109
	v_mul_f32_e32 v120, v111, v111
	v_cvt_pk_bf16_f32 v96, v108, v109
	v_cvt_pk_bf16_f32 v97, v110, v111
	v_mul_f32_e32 v109, v105, v105
	v_mul_f32_e32 v111, v107, v107
	v_mul_f32_e32 v121, v101, v101
	v_mul_f32_e32 v122, v103, v103
	v_fmac_f32_e32 v115, v108, v108
	v_fmac_f32_e32 v120, v110, v110
	v_fmac_f32_e32 v109, v104, v104
	v_fmac_f32_e32 v111, v106, v106
	v_mul_f32_e32 v123, v119, v119
	v_mul_f32_e32 v124, v99, v99
	global_store_dwordx2 v[116:117], v[96:97], off
	v_cvt_pk_bf16_f32 v96, v104, v105
	v_fmac_f32_e32 v121, v100, v100
	v_fmac_f32_e32 v122, v102, v102
	v_add_f32_e32 v97, v115, v120
	v_add_f32_e32 v104, v109, v111
	v_fmac_f32_e32 v123, v118, v118
	v_fmac_f32_e32 v124, v98, v98
	v_add_f32_e32 v105, v121, v122
	v_add_f32_e32 v97, v97, v104
	v_add_f32_e32 v97, v97, v105
	v_add_f32_e32 v104, v123, v124
	v_add_f32_e32 v104, v97, v104
	v_mov_b32_e32 v105, v104
	s_nop 1
	v_permlane16_swap_b32_e32 v104, v105
	v_cvt_pk_bf16_f32 v97, v106, v107
	global_store_dwordx2 v[116:117], v[96:97], off offset:32
	v_cvt_pk_bf16_f32 v100, v100, v101
	v_cvt_pk_bf16_f32 v101, v102, v103
	s_waitcnt lgkmcnt(0)
	v_add_f32_e32 v96, v104, v105
	v_mov_b32_e32 v97, v96
	s_nop 1
	v_permlane32_swap_b32_e32 v96, v97
	global_store_dwordx2 v[116:117], v[100:101], off offset:256
	v_cvt_pk_bf16_f32 v100, v118, v119
	v_cvt_pk_bf16_f32 v101, v98, v99
	global_store_dwordx2 v[116:117], v[100:101], off offset:288
	s_and_saveexec_b64 s[54:55], s[0:1]
	s_cbranch_execz .LBB0_552
	v_lshlrev_b64 v[98:99], 7, v[112:113]
	v_lshl_add_u64 v[98:99], s[26:27], 0, v[98:99]
	v_lshl_add_u64 v[98:99], s[50:51], 2, v[98:99]
	s_lshl_b32 s12, s64, 2
	v_lshl_add_u64 v[98:99], v[98:99], 0, s[12:13]
	s_waitcnt lgkmcnt(0)
	v_add_f32_e32 v96, v96, v97
	global_store_dword v[98:99], v96, off
.LBB0_552:
	s_or_b64 exec, exec, s[54:55]
	v_or_b32_e32 v96, 32, v142
	s_waitcnt lgkmcnt(0)
	v_ashrrev_i32_e32 v97, 31, v96
	v_lshlrev_b64 v[98:99], 11, v[96:97]
	v_lshl_add_u64 v[98:99], v[98:99], 0, v[140:141]
	v_lshlrev_b64 v[98:99], 1, v[98:99]
	v_lshl_add_u64 v[100:101], s[18:19], 0, v[98:99]
	global_load_dwordx2 v[102:103], v[100:101], off
	global_load_dwordx2 v[104:105], v[100:101], off offset:32
	global_load_dwordx2 v[106:107], v[100:101], off offset:256
	s_nop 0
	global_load_dwordx2 v[100:101], v[100:101], off offset:288
	v_lshl_add_u64 v[98:99], s[10:11], 0, v[98:99]
	s_waitcnt vmcnt(3)
	v_lshlrev_b32_e32 v108, 16, v102
	v_and_b32_e32 v109, 0xffff0000, v102
	v_lshlrev_b32_e32 v102, 16, v103
	v_and_b32_e32 v103, 0xffff0000, v103
	s_waitcnt vmcnt(2)
	v_lshlrev_b32_e32 v110, 16, v104
	v_and_b32_e32 v111, 0xffff0000, v104
	v_lshlrev_b32_e32 v104, 16, v105
	v_and_b32_e32 v105, 0xffff0000, v105
	s_waitcnt vmcnt(1)
	v_lshlrev_b32_e32 v112, 16, v106
	v_and_b32_e32 v113, 0xffff0000, v106
	v_lshlrev_b32_e32 v106, 16, v107
	v_and_b32_e32 v107, 0xffff0000, v107
	s_waitcnt vmcnt(0)
	v_lshlrev_b32_e32 v116, 16, v100
	v_and_b32_e32 v117, 0xffff0000, v100
	v_lshlrev_b32_e32 v100, 16, v101
	v_and_b32_e32 v101, 0xffff0000, v101
	v_pk_add_f32 v[94:95], v[94:95], v[102:103]
	v_pk_add_f32 v[92:93], v[92:93], v[108:109]
	v_pk_add_f32 v[90:91], v[90:91], v[104:105]
	v_pk_add_f32 v[88:89], v[88:89], v[110:111]
	v_pk_add_f32 v[86:87], v[86:87], v[106:107]
	v_pk_add_f32 v[84:85], v[84:85], v[112:113]
	v_pk_add_f32 v[82:83], v[82:83], v[100:101]
	v_pk_add_f32 v[100:101], v[80:81], v[116:117]
	v_mul_f32_e32 v102, v93, v93
	v_mul_f32_e32 v103, v95, v95
	v_cvt_pk_bf16_f32 v80, v92, v93
	v_cvt_pk_bf16_f32 v81, v94, v95
	v_mul_f32_e32 v93, v89, v89
	v_mul_f32_e32 v95, v91, v91
	v_mul_f32_e32 v104, v85, v85
	v_mul_f32_e32 v105, v87, v87
	v_fmac_f32_e32 v102, v92, v92
	v_fmac_f32_e32 v103, v94, v94
	v_fmac_f32_e32 v93, v88, v88
	v_fmac_f32_e32 v95, v90, v90
	v_mul_f32_e32 v106, v101, v101
	v_mul_f32_e32 v107, v83, v83
	global_store_dwordx2 v[98:99], v[80:81], off
	v_cvt_pk_bf16_f32 v80, v88, v89
	v_fmac_f32_e32 v104, v84, v84
	v_fmac_f32_e32 v105, v86, v86
	v_add_f32_e32 v81, v102, v103
	v_add_f32_e32 v88, v93, v95
	v_fmac_f32_e32 v106, v100, v100
	v_fmac_f32_e32 v107, v82, v82
	v_add_f32_e32 v89, v104, v105
	v_add_f32_e32 v81, v81, v88
	v_add_f32_e32 v81, v81, v89
	v_add_f32_e32 v88, v106, v107
	v_add_f32_e32 v88, v81, v88
	v_mov_b32_e32 v89, v88
	s_nop 1
	v_permlane16_swap_b32_e32 v88, v89
	v_cvt_pk_bf16_f32 v81, v90, v91
	global_store_dwordx2 v[98:99], v[80:81], off offset:32
	v_cvt_pk_bf16_f32 v84, v84, v85
	v_cvt_pk_bf16_f32 v85, v86, v87
	s_waitcnt lgkmcnt(0)
	v_add_f32_e32 v80, v88, v89
	v_mov_b32_e32 v81, v80
	s_nop 1
	v_permlane32_swap_b32_e32 v80, v81
	global_store_dwordx2 v[98:99], v[84:85], off offset:256
	v_cvt_pk_bf16_f32 v84, v100, v101
	v_cvt_pk_bf16_f32 v85, v82, v83
	global_store_dwordx2 v[98:99], v[84:85], off offset:288
	s_and_saveexec_b64 s[54:55], s[0:1]
	s_cbranch_execz .LBB0_554
	v_lshlrev_b64 v[82:83], 7, v[96:97]
	v_lshl_add_u64 v[82:83], s[26:27], 0, v[82:83]
	v_lshl_add_u64 v[82:83], s[50:51], 2, v[82:83]
	s_lshl_b32 s12, s64, 2
	v_lshl_add_u64 v[82:83], v[82:83], 0, s[12:13]
	s_waitcnt lgkmcnt(0)
	v_add_f32_e32 v80, v80, v81
	global_store_dword v[82:83], v80, off
.LBB0_554:
	s_or_b64 exec, exec, s[54:55]
	v_or_b32_e32 v80, 48, v142
	s_waitcnt lgkmcnt(0)
	v_ashrrev_i32_e32 v81, 31, v80
	v_lshlrev_b64 v[82:83], 11, v[80:81]
	v_lshl_add_u64 v[82:83], v[82:83], 0, v[140:141]
	v_lshlrev_b64 v[82:83], 1, v[82:83]
	v_lshl_add_u64 v[84:85], s[18:19], 0, v[82:83]
	global_load_dwordx2 v[86:87], v[84:85], off
	global_load_dwordx2 v[88:89], v[84:85], off offset:32
	global_load_dwordx2 v[90:91], v[84:85], off offset:256
	s_nop 0
	global_load_dwordx2 v[84:85], v[84:85], off offset:288
	v_lshl_add_u64 v[82:83], s[10:11], 0, v[82:83]
	s_waitcnt vmcnt(3)
	v_lshlrev_b32_e32 v92, 16, v86
	v_and_b32_e32 v93, 0xffff0000, v86
	v_lshlrev_b32_e32 v86, 16, v87
	v_and_b32_e32 v87, 0xffff0000, v87
	s_waitcnt vmcnt(2)
	v_lshlrev_b32_e32 v94, 16, v88
	v_and_b32_e32 v95, 0xffff0000, v88
	v_lshlrev_b32_e32 v88, 16, v89
	v_and_b32_e32 v89, 0xffff0000, v89
	s_waitcnt vmcnt(1)
	v_lshlrev_b32_e32 v96, 16, v90
	v_and_b32_e32 v97, 0xffff0000, v90
	v_lshlrev_b32_e32 v90, 16, v91
	v_and_b32_e32 v91, 0xffff0000, v91
	s_waitcnt vmcnt(0)
	v_lshlrev_b32_e32 v98, 16, v84
	v_and_b32_e32 v99, 0xffff0000, v84
	v_lshlrev_b32_e32 v84, 16, v85
	v_and_b32_e32 v85, 0xffff0000, v85
	v_pk_add_f32 v[78:79], v[78:79], v[86:87]
	v_pk_add_f32 v[76:77], v[76:77], v[92:93]
	v_pk_add_f32 v[74:75], v[74:75], v[88:89]
	v_pk_add_f32 v[72:73], v[72:73], v[94:95]
	v_pk_add_f32 v[70:71], v[70:71], v[90:91]
	v_pk_add_f32 v[68:69], v[68:69], v[96:97]
	v_pk_add_f32 v[66:67], v[66:67], v[84:85]
	v_pk_add_f32 v[84:85], v[64:65], v[98:99]
	v_mul_f32_e32 v86, v77, v77
	v_mul_f32_e32 v87, v79, v79
	v_cvt_pk_bf16_f32 v64, v76, v77
	v_cvt_pk_bf16_f32 v65, v78, v79
	v_mul_f32_e32 v77, v73, v73
	v_mul_f32_e32 v79, v75, v75
	v_mul_f32_e32 v88, v69, v69
	v_mul_f32_e32 v89, v71, v71
	v_fmac_f32_e32 v86, v76, v76
	v_fmac_f32_e32 v87, v78, v78
	v_fmac_f32_e32 v77, v72, v72
	v_fmac_f32_e32 v79, v74, v74
	v_mul_f32_e32 v90, v85, v85
	v_mul_f32_e32 v91, v67, v67
	global_store_dwordx2 v[82:83], v[64:65], off
	v_cvt_pk_bf16_f32 v64, v72, v73
	v_fmac_f32_e32 v88, v68, v68
	v_fmac_f32_e32 v89, v70, v70
	v_add_f32_e32 v65, v86, v87
	v_add_f32_e32 v72, v77, v79
	v_fmac_f32_e32 v90, v84, v84
	v_fmac_f32_e32 v91, v66, v66
	v_add_f32_e32 v73, v88, v89
	v_add_f32_e32 v65, v65, v72
	v_add_f32_e32 v65, v65, v73
	v_add_f32_e32 v72, v90, v91
	v_add_f32_e32 v72, v65, v72
	v_mov_b32_e32 v73, v72
	s_nop 1
	v_permlane16_swap_b32_e32 v72, v73
	v_cvt_pk_bf16_f32 v65, v74, v75
	global_store_dwordx2 v[82:83], v[64:65], off offset:32
	v_cvt_pk_bf16_f32 v68, v68, v69
	v_cvt_pk_bf16_f32 v69, v70, v71
	s_waitcnt lgkmcnt(0)
	v_add_f32_e32 v64, v72, v73
	v_mov_b32_e32 v65, v64
	s_nop 1
	v_permlane32_swap_b32_e32 v64, v65
	global_store_dwordx2 v[82:83], v[68:69], off offset:256
	v_cvt_pk_bf16_f32 v68, v84, v85
	v_cvt_pk_bf16_f32 v69, v66, v67
	global_store_dwordx2 v[82:83], v[68:69], off offset:288
	s_and_saveexec_b64 s[54:55], s[0:1]
	s_cbranch_execz .LBB0_556
	v_lshlrev_b64 v[66:67], 7, v[80:81]
	v_lshl_add_u64 v[66:67], s[26:27], 0, v[66:67]
	v_lshl_add_u64 v[66:67], s[50:51], 2, v[66:67]
	s_lshl_b32 s12, s64, 2
	v_lshl_add_u64 v[66:67], v[66:67], 0, s[12:13]
	s_waitcnt lgkmcnt(0)
	v_add_f32_e32 v64, v64, v65
	global_store_dword v[66:67], v64, off
.LBB0_556:
	s_or_b64 exec, exec, s[54:55]
	v_add_u32_e32 v64, 0x80, v142
	s_waitcnt lgkmcnt(0)
	v_ashrrev_i32_e32 v65, 31, v64
	v_lshlrev_b64 v[66:67], 11, v[64:65]
	v_lshl_add_u64 v[66:67], v[66:67], 0, v[140:141]
	v_lshlrev_b64 v[66:67], 1, v[66:67]
	v_lshl_add_u64 v[68:69], s[18:19], 0, v[66:67]
	global_load_dwordx2 v[70:71], v[68:69], off
	global_load_dwordx2 v[72:73], v[68:69], off offset:32
	global_load_dwordx2 v[74:75], v[68:69], off offset:256
	s_nop 0
	global_load_dwordx2 v[68:69], v[68:69], off offset:288
	v_lshl_add_u64 v[66:67], s[10:11], 0, v[66:67]
	s_waitcnt vmcnt(3)
	v_lshlrev_b32_e32 v76, 16, v70
	v_and_b32_e32 v77, 0xffff0000, v70
	v_lshlrev_b32_e32 v70, 16, v71
	v_and_b32_e32 v71, 0xffff0000, v71
	s_waitcnt vmcnt(2)
	v_lshlrev_b32_e32 v78, 16, v72
	v_and_b32_e32 v79, 0xffff0000, v72
	v_lshlrev_b32_e32 v72, 16, v73
	v_and_b32_e32 v73, 0xffff0000, v73
	s_waitcnt vmcnt(1)
	v_lshlrev_b32_e32 v80, 16, v74
	v_and_b32_e32 v81, 0xffff0000, v74
	v_lshlrev_b32_e32 v74, 16, v75
	v_and_b32_e32 v75, 0xffff0000, v75
	s_waitcnt vmcnt(0)
	v_lshlrev_b32_e32 v82, 16, v68
	v_and_b32_e32 v83, 0xffff0000, v68
	v_lshlrev_b32_e32 v68, 16, v69
	v_and_b32_e32 v69, 0xffff0000, v69
	v_pk_add_f32 v[62:63], v[62:63], v[70:71]
	v_pk_add_f32 v[60:61], v[60:61], v[76:77]
	v_pk_add_f32 v[58:59], v[58:59], v[72:73]
	v_pk_add_f32 v[56:57], v[56:57], v[78:79]
	v_pk_add_f32 v[54:55], v[54:55], v[74:75]
	v_pk_add_f32 v[52:53], v[52:53], v[80:81]
	v_pk_add_f32 v[50:51], v[50:51], v[68:69]
	v_pk_add_f32 v[68:69], v[48:49], v[82:83]
	v_mul_f32_e32 v70, v61, v61
	v_mul_f32_e32 v71, v63, v63
	v_cvt_pk_bf16_f32 v48, v60, v61
	v_cvt_pk_bf16_f32 v49, v62, v63
	v_mul_f32_e32 v61, v57, v57
	v_mul_f32_e32 v63, v59, v59
	v_mul_f32_e32 v72, v53, v53
	v_mul_f32_e32 v73, v55, v55
	v_fmac_f32_e32 v70, v60, v60
	v_fmac_f32_e32 v71, v62, v62
	v_fmac_f32_e32 v61, v56, v56
	v_fmac_f32_e32 v63, v58, v58
	v_mul_f32_e32 v74, v69, v69
	v_mul_f32_e32 v75, v51, v51
	global_store_dwordx2 v[66:67], v[48:49], off
	v_cvt_pk_bf16_f32 v48, v56, v57
	v_fmac_f32_e32 v72, v52, v52
	v_fmac_f32_e32 v73, v54, v54
	v_add_f32_e32 v49, v70, v71
	v_add_f32_e32 v56, v61, v63
	v_fmac_f32_e32 v74, v68, v68
	v_fmac_f32_e32 v75, v50, v50
	v_add_f32_e32 v57, v72, v73
	v_add_f32_e32 v49, v49, v56
	v_add_f32_e32 v49, v49, v57
	v_add_f32_e32 v56, v74, v75
	v_add_f32_e32 v56, v49, v56
	v_mov_b32_e32 v57, v56
	s_nop 1
	v_permlane16_swap_b32_e32 v56, v57
	v_cvt_pk_bf16_f32 v49, v58, v59
	global_store_dwordx2 v[66:67], v[48:49], off offset:32
	v_cvt_pk_bf16_f32 v52, v52, v53
	v_cvt_pk_bf16_f32 v53, v54, v55
	s_waitcnt lgkmcnt(0)
	v_add_f32_e32 v48, v56, v57
	v_mov_b32_e32 v49, v48
	s_nop 1
	v_permlane32_swap_b32_e32 v48, v49
	global_store_dwordx2 v[66:67], v[52:53], off offset:256
	v_cvt_pk_bf16_f32 v52, v68, v69
	v_cvt_pk_bf16_f32 v53, v50, v51
	global_store_dwordx2 v[66:67], v[52:53], off offset:288
	s_and_saveexec_b64 s[54:55], s[0:1]
	s_cbranch_execz .LBB0_558
	v_lshlrev_b64 v[50:51], 7, v[64:65]
	v_lshl_add_u64 v[50:51], s[26:27], 0, v[50:51]
	v_lshl_add_u64 v[50:51], s[50:51], 2, v[50:51]
	s_lshl_b32 s12, s64, 2
	v_lshl_add_u64 v[50:51], v[50:51], 0, s[12:13]
	s_waitcnt lgkmcnt(0)
	v_add_f32_e32 v48, v48, v49
	global_store_dword v[50:51], v48, off
.LBB0_558:
	s_or_b64 exec, exec, s[54:55]
	v_add_u32_e32 v48, 0x90, v142
	s_waitcnt lgkmcnt(0)
	v_ashrrev_i32_e32 v49, 31, v48
	v_lshlrev_b64 v[50:51], 11, v[48:49]
	v_lshl_add_u64 v[50:51], v[50:51], 0, v[140:141]
	v_lshlrev_b64 v[50:51], 1, v[50:51]
	v_lshl_add_u64 v[52:53], s[18:19], 0, v[50:51]
	global_load_dwordx2 v[54:55], v[52:53], off
	global_load_dwordx2 v[56:57], v[52:53], off offset:32
	global_load_dwordx2 v[58:59], v[52:53], off offset:256
	s_nop 0
	global_load_dwordx2 v[52:53], v[52:53], off offset:288
	v_lshl_add_u64 v[50:51], s[10:11], 0, v[50:51]
	s_waitcnt vmcnt(3)
	v_lshlrev_b32_e32 v60, 16, v54
	v_and_b32_e32 v61, 0xffff0000, v54
	v_lshlrev_b32_e32 v54, 16, v55
	v_and_b32_e32 v55, 0xffff0000, v55
	s_waitcnt vmcnt(2)
	v_lshlrev_b32_e32 v62, 16, v56
	v_and_b32_e32 v63, 0xffff0000, v56
	v_lshlrev_b32_e32 v56, 16, v57
	v_and_b32_e32 v57, 0xffff0000, v57
	s_waitcnt vmcnt(1)
	v_lshlrev_b32_e32 v64, 16, v58
	v_and_b32_e32 v65, 0xffff0000, v58
	v_lshlrev_b32_e32 v58, 16, v59
	v_and_b32_e32 v59, 0xffff0000, v59
	s_waitcnt vmcnt(0)
	v_lshlrev_b32_e32 v66, 16, v52
	v_and_b32_e32 v67, 0xffff0000, v52
	v_lshlrev_b32_e32 v52, 16, v53
	v_and_b32_e32 v53, 0xffff0000, v53
	v_pk_add_f32 v[46:47], v[46:47], v[54:55]
	v_pk_add_f32 v[44:45], v[44:45], v[60:61]
	v_pk_add_f32 v[42:43], v[42:43], v[56:57]
	v_pk_add_f32 v[40:41], v[40:41], v[62:63]
	v_pk_add_f32 v[38:39], v[38:39], v[58:59]
	v_pk_add_f32 v[36:37], v[36:37], v[64:65]
	v_pk_add_f32 v[34:35], v[34:35], v[52:53]
	v_pk_add_f32 v[52:53], v[32:33], v[66:67]
	v_mul_f32_e32 v54, v45, v45
	v_mul_f32_e32 v55, v47, v47
	v_cvt_pk_bf16_f32 v32, v44, v45
	v_cvt_pk_bf16_f32 v33, v46, v47
	v_mul_f32_e32 v45, v41, v41
	v_mul_f32_e32 v47, v43, v43
	v_mul_f32_e32 v56, v37, v37
	v_mul_f32_e32 v57, v39, v39
	v_fmac_f32_e32 v54, v44, v44
	v_fmac_f32_e32 v55, v46, v46
	v_fmac_f32_e32 v45, v40, v40
	v_fmac_f32_e32 v47, v42, v42
	v_mul_f32_e32 v58, v53, v53
	v_mul_f32_e32 v59, v35, v35
	global_store_dwordx2 v[50:51], v[32:33], off
	v_cvt_pk_bf16_f32 v32, v40, v41
	v_fmac_f32_e32 v56, v36, v36
	v_fmac_f32_e32 v57, v38, v38
	v_add_f32_e32 v33, v54, v55
	v_add_f32_e32 v40, v45, v47
	v_fmac_f32_e32 v58, v52, v52
	v_fmac_f32_e32 v59, v34, v34
	v_add_f32_e32 v41, v56, v57
	v_add_f32_e32 v33, v33, v40
	v_add_f32_e32 v33, v33, v41
	v_add_f32_e32 v40, v58, v59
	v_add_f32_e32 v40, v33, v40
	v_mov_b32_e32 v41, v40
	s_nop 1
	v_permlane16_swap_b32_e32 v40, v41
	v_cvt_pk_bf16_f32 v33, v42, v43
	global_store_dwordx2 v[50:51], v[32:33], off offset:32
	v_cvt_pk_bf16_f32 v36, v36, v37
	v_cvt_pk_bf16_f32 v37, v38, v39
	s_waitcnt lgkmcnt(0)
	v_add_f32_e32 v32, v40, v41
	v_mov_b32_e32 v33, v32
	s_nop 1
	v_permlane32_swap_b32_e32 v32, v33
	global_store_dwordx2 v[50:51], v[36:37], off offset:256
	v_cvt_pk_bf16_f32 v36, v52, v53
	v_cvt_pk_bf16_f32 v37, v34, v35
	global_store_dwordx2 v[50:51], v[36:37], off offset:288
	s_and_saveexec_b64 s[54:55], s[0:1]
	s_cbranch_execz .LBB0_560
	v_lshlrev_b64 v[34:35], 7, v[48:49]
	v_lshl_add_u64 v[34:35], s[26:27], 0, v[34:35]
	v_lshl_add_u64 v[34:35], s[50:51], 2, v[34:35]
	s_lshl_b32 s12, s64, 2
	v_lshl_add_u64 v[34:35], v[34:35], 0, s[12:13]
	s_waitcnt lgkmcnt(0)
	v_add_f32_e32 v32, v32, v33
	global_store_dword v[34:35], v32, off
.LBB0_560:
	s_or_b64 exec, exec, s[54:55]
	v_add_u32_e32 v32, 0xa0, v142
	s_waitcnt lgkmcnt(0)
	v_ashrrev_i32_e32 v33, 31, v32
	v_lshlrev_b64 v[34:35], 11, v[32:33]
	v_lshl_add_u64 v[34:35], v[34:35], 0, v[140:141]
	v_lshlrev_b64 v[34:35], 1, v[34:35]
	v_lshl_add_u64 v[36:37], s[18:19], 0, v[34:35]
	global_load_dwordx2 v[38:39], v[36:37], off
	global_load_dwordx2 v[40:41], v[36:37], off offset:32
	global_load_dwordx2 v[42:43], v[36:37], off offset:256
	s_nop 0
	global_load_dwordx2 v[36:37], v[36:37], off offset:288
	v_lshl_add_u64 v[34:35], s[10:11], 0, v[34:35]
	s_waitcnt vmcnt(3)
	v_lshlrev_b32_e32 v44, 16, v38
	v_and_b32_e32 v45, 0xffff0000, v38
	v_lshlrev_b32_e32 v38, 16, v39
	v_and_b32_e32 v39, 0xffff0000, v39
	s_waitcnt vmcnt(2)
	v_lshlrev_b32_e32 v46, 16, v40
	v_and_b32_e32 v47, 0xffff0000, v40
	v_lshlrev_b32_e32 v40, 16, v41
	v_and_b32_e32 v41, 0xffff0000, v41
	s_waitcnt vmcnt(1)
	v_lshlrev_b32_e32 v48, 16, v42
	v_and_b32_e32 v49, 0xffff0000, v42
	v_lshlrev_b32_e32 v42, 16, v43
	v_and_b32_e32 v43, 0xffff0000, v43
	s_waitcnt vmcnt(0)
	v_lshlrev_b32_e32 v50, 16, v36
	v_and_b32_e32 v51, 0xffff0000, v36
	v_lshlrev_b32_e32 v36, 16, v37
	v_and_b32_e32 v37, 0xffff0000, v37
	v_pk_add_f32 v[30:31], v[30:31], v[38:39]
	v_pk_add_f32 v[28:29], v[28:29], v[44:45]
	v_pk_add_f32 v[26:27], v[26:27], v[40:41]
	v_pk_add_f32 v[24:25], v[24:25], v[46:47]
	v_pk_add_f32 v[22:23], v[22:23], v[42:43]
	v_pk_add_f32 v[20:21], v[20:21], v[48:49]
	v_pk_add_f32 v[18:19], v[18:19], v[36:37]
	v_pk_add_f32 v[36:37], v[16:17], v[50:51]
	v_mul_f32_e32 v38, v29, v29
	v_mul_f32_e32 v39, v31, v31
	v_cvt_pk_bf16_f32 v16, v28, v29
	v_cvt_pk_bf16_f32 v17, v30, v31
	v_mul_f32_e32 v29, v25, v25
	v_mul_f32_e32 v31, v27, v27
	v_mul_f32_e32 v40, v21, v21
	v_mul_f32_e32 v41, v23, v23
	v_fmac_f32_e32 v38, v28, v28
	v_fmac_f32_e32 v39, v30, v30
	v_fmac_f32_e32 v29, v24, v24
	v_fmac_f32_e32 v31, v26, v26
	v_mul_f32_e32 v42, v37, v37
	v_mul_f32_e32 v43, v19, v19
	global_store_dwordx2 v[34:35], v[16:17], off
	v_cvt_pk_bf16_f32 v16, v24, v25
	v_fmac_f32_e32 v40, v20, v20
	v_fmac_f32_e32 v41, v22, v22
	v_add_f32_e32 v17, v38, v39
	v_add_f32_e32 v24, v29, v31
	v_fmac_f32_e32 v42, v36, v36
	v_fmac_f32_e32 v43, v18, v18
	v_add_f32_e32 v25, v40, v41
	v_add_f32_e32 v17, v17, v24
	v_add_f32_e32 v17, v17, v25
	v_add_f32_e32 v24, v42, v43
	v_add_f32_e32 v24, v17, v24
	v_mov_b32_e32 v25, v24
	s_nop 1
	v_permlane16_swap_b32_e32 v24, v25
	v_cvt_pk_bf16_f32 v17, v26, v27
	global_store_dwordx2 v[34:35], v[16:17], off offset:32
	v_cvt_pk_bf16_f32 v20, v20, v21
	v_cvt_pk_bf16_f32 v21, v22, v23
	s_waitcnt lgkmcnt(0)
	v_add_f32_e32 v16, v24, v25
	v_mov_b32_e32 v17, v16
	s_nop 1
	v_permlane32_swap_b32_e32 v16, v17
	global_store_dwordx2 v[34:35], v[20:21], off offset:256
	v_cvt_pk_bf16_f32 v20, v36, v37
	v_cvt_pk_bf16_f32 v21, v18, v19
	global_store_dwordx2 v[34:35], v[20:21], off offset:288
	s_and_saveexec_b64 s[54:55], s[0:1]
	s_cbranch_execz .LBB0_562
	v_lshlrev_b64 v[18:19], 7, v[32:33]
	v_lshl_add_u64 v[18:19], s[26:27], 0, v[18:19]
	v_lshl_add_u64 v[18:19], s[50:51], 2, v[18:19]
	s_lshl_b32 s12, s64, 2
	v_lshl_add_u64 v[18:19], v[18:19], 0, s[12:13]
	s_waitcnt lgkmcnt(0)
	v_add_f32_e32 v16, v16, v17
	global_store_dword v[18:19], v16, off
.LBB0_562:
	s_or_b64 exec, exec, s[54:55]
	v_add_u32_e32 v16, 0xb0, v142
	s_waitcnt lgkmcnt(0)
	v_ashrrev_i32_e32 v17, 31, v16
	v_lshlrev_b64 v[18:19], 11, v[16:17]
	v_lshl_add_u64 v[18:19], v[18:19], 0, v[140:141]
	v_lshlrev_b64 v[18:19], 1, v[18:19]
	v_lshl_add_u64 v[20:21], s[18:19], 0, v[18:19]
	global_load_dwordx2 v[22:23], v[20:21], off
	global_load_dwordx2 v[24:25], v[20:21], off offset:32
	global_load_dwordx2 v[26:27], v[20:21], off offset:256
	s_nop 0
	global_load_dwordx2 v[20:21], v[20:21], off offset:288
	v_lshl_add_u64 v[18:19], s[10:11], 0, v[18:19]
	s_waitcnt vmcnt(3)
	v_lshlrev_b32_e32 v28, 16, v22
	v_and_b32_e32 v29, 0xffff0000, v22
	v_lshlrev_b32_e32 v22, 16, v23
	v_and_b32_e32 v23, 0xffff0000, v23
	s_waitcnt vmcnt(2)
	v_lshlrev_b32_e32 v30, 16, v24
	v_and_b32_e32 v31, 0xffff0000, v24
	v_lshlrev_b32_e32 v24, 16, v25
	v_and_b32_e32 v25, 0xffff0000, v25
	s_waitcnt vmcnt(1)
	v_lshlrev_b32_e32 v32, 16, v26
	v_and_b32_e32 v33, 0xffff0000, v26
	v_lshlrev_b32_e32 v26, 16, v27
	v_and_b32_e32 v27, 0xffff0000, v27
	s_waitcnt vmcnt(0)
	v_lshlrev_b32_e32 v34, 16, v20
	v_and_b32_e32 v35, 0xffff0000, v20
	v_lshlrev_b32_e32 v20, 16, v21
	v_and_b32_e32 v21, 0xffff0000, v21
	v_pk_add_f32 v[14:15], v[14:15], v[22:23]
	v_pk_add_f32 v[12:13], v[12:13], v[28:29]
	v_pk_add_f32 v[10:11], v[10:11], v[24:25]
	v_pk_add_f32 v[8:9], v[8:9], v[30:31]
	v_pk_add_f32 v[6:7], v[6:7], v[26:27]
	v_pk_add_f32 v[4:5], v[4:5], v[32:33]
	v_pk_add_f32 v[2:3], v[2:3], v[20:21]
	v_pk_add_f32 v[20:21], v[0:1], v[34:35]
	v_mul_f32_e32 v22, v13, v13
	v_mul_f32_e32 v23, v15, v15
	v_cvt_pk_bf16_f32 v0, v12, v13
	v_cvt_pk_bf16_f32 v1, v14, v15
	v_mul_f32_e32 v13, v9, v9
	v_mul_f32_e32 v15, v11, v11
	v_mul_f32_e32 v24, v5, v5
	v_mul_f32_e32 v25, v7, v7
	v_fmac_f32_e32 v22, v12, v12
	v_fmac_f32_e32 v23, v14, v14
	v_fmac_f32_e32 v13, v8, v8
	v_fmac_f32_e32 v15, v10, v10
	v_mul_f32_e32 v26, v21, v21
	v_mul_f32_e32 v27, v3, v3
	global_store_dwordx2 v[18:19], v[0:1], off
	v_cvt_pk_bf16_f32 v0, v8, v9
	v_fmac_f32_e32 v24, v4, v4
	v_fmac_f32_e32 v25, v6, v6
	v_add_f32_e32 v1, v22, v23
	v_add_f32_e32 v8, v13, v15
	v_fmac_f32_e32 v26, v20, v20
	v_fmac_f32_e32 v27, v2, v2
	v_add_f32_e32 v9, v24, v25
	v_add_f32_e32 v1, v1, v8
	v_add_f32_e32 v1, v1, v9
	v_add_f32_e32 v8, v26, v27
	v_add_f32_e32 v8, v1, v8
	v_mov_b32_e32 v9, v8
	s_nop 1
	v_permlane16_swap_b32_e32 v8, v9
	v_cvt_pk_bf16_f32 v1, v10, v11
	global_store_dwordx2 v[18:19], v[0:1], off offset:32
	v_cvt_pk_bf16_f32 v4, v4, v5
	v_cvt_pk_bf16_f32 v5, v6, v7
	s_waitcnt lgkmcnt(0)
	v_add_f32_e32 v0, v8, v9
	v_mov_b32_e32 v1, v0
	s_nop 1
	v_permlane32_swap_b32_e32 v0, v1
	global_store_dwordx2 v[18:19], v[4:5], off offset:256
	v_cvt_pk_bf16_f32 v4, v20, v21
	v_cvt_pk_bf16_f32 v5, v2, v3
	global_store_dwordx2 v[18:19], v[4:5], off offset:288
	s_and_saveexec_b64 s[54:55], s[0:1]
	s_cbranch_execz .LBB0_564
	v_lshlrev_b64 v[2:3], 7, v[16:17]
	v_lshl_add_u64 v[2:3], s[26:27], 0, v[2:3]
	v_lshl_add_u64 v[2:3], s[50:51], 2, v[2:3]
	s_lshl_b32 s12, s64, 2
	v_lshl_add_u64 v[2:3], v[2:3], 0, s[12:13]
	s_waitcnt lgkmcnt(0)
	v_add_f32_e32 v0, v0, v1
	global_store_dword v[2:3], v0, off
